# input-projection GEMM epilogue: the 8 per-row-block rstd chains (load, drain, 2 bpermutes, rsqrt) batched up front with counted waits; row blocks then scale/convert/store without vmcnt waits
# speedup vs baseline: 1.0666x; 1.0140x over previous
; __device__ __forceinline__ float rstd_from_ss(const float* ssrow, int fq) {
;     const f32x4 a = ((const f32x4*)ssrow)[fq];
;     float s = (a[0] + a[1]) + (a[2] + a[3]);
;     s += __shfl_xor(s, 16); s += __shfl_xor(s, 32);
;     return rsqrtf(s * (1.0f / 1024.0f) + 1e-6f);
; }
;     __device__ __forceinline__ void operator()(const f32x4 (&acc)[2][2][4][2], const Unit& u, int wr, int wc, int fr, int fq) const {
;     ...
; #pragma unroll
;         for (int ai = 0; ai < 2; ++ai)
; #pragma unroll
;             for (int m = 0; m < 4; ++m) {
;                 int row = lrow0 + ai * HALF + m * 16; asm volatile("" : "+v"(row));
;                 const float rs = rstd_from_ss(SS + (size_t)row * 16, fq);
;                 if (pn < 32) {
.LBB0_374:
	v_add_u32_e32 v170, s7, v166
	v_ashrrev_i32_e32 v171, 31, v170
	v_lshlrev_b64 v[172:173], 6, v[170:171]
	s_mov_b64 s[40:41], 0x2000
	v_lshl_add_u64 v[172:173], v[146:147], 0, v[172:173]
	v_add_u32_e32 v2, s6, v168
	v_lshl_add_u64 v[174:175], v[172:173], 0, s[40:41]
	global_load_dwordx4 v[210:213], v[172:173], off
	global_load_dwordx4 v[214:217], v[172:173], off offset:1024
	global_load_dwordx4 v[218:221], v[172:173], off offset:2048
	global_load_dwordx4 v[222:225], v[172:173], off offset:3072
	global_load_dwordx4 v[226:229], v[174:175], off
	global_load_dwordx4 v[230:233], v[174:175], off offset:1024
	global_load_dwordx4 v[234:237], v[174:175], off offset:2048
	global_load_dwordx4 v[238:241], v[174:175], off offset:3072
	v_lshl_add_u64 v[156:157], v[2:3], 1, s[14:15]
	v_mad_i64_i32 v[160:161], s[42:43], s36, v170, 0
	v_lshl_add_u64 v[158:159], v[2:3], 2, s[12:13]
	v_lshl_add_u64 v[162:163], s[38:39], 0, v[170:171]
	v_lshl_add_u64 v[156:157], v[160:161], 1, v[156:157]
	v_lshlrev_b64 v[162:163], 12, v[162:163]
	v_lshlrev_b64 v[160:161], 6, v[170:171]
	v_lshl_add_u64 v[158:159], v[158:159], 0, v[162:163]
	v_lshl_add_u64 v[160:161], v[148:149], 0, v[160:161]
	v_lshl_add_u64 v[162:163], v[160:161], 0, s[40:41]
	s_waitcnt vmcnt(4)
	v_add_f32_e32 v210, v211, v210
	v_add_f32_e32 v214, v215, v214
	v_add_f32_e32 v218, v219, v218
	v_add_f32_e32 v222, v223, v222
	v_add_f32_e32 v212, v212, v213
	v_add_f32_e32 v216, v216, v217
	v_add_f32_e32 v220, v220, v221
	v_add_f32_e32 v224, v224, v225
	v_add_f32_e32 v210, v210, v212
	v_add_f32_e32 v214, v214, v216
	v_add_f32_e32 v218, v218, v220
	v_add_f32_e32 v222, v222, v224
	ds_bpermute_b32 v211, v199, v210
	ds_bpermute_b32 v215, v199, v214
	ds_bpermute_b32 v219, v199, v218
	ds_bpermute_b32 v223, v199, v222
	s_waitcnt vmcnt(0)
	v_add_f32_e32 v226, v227, v226
	v_add_f32_e32 v230, v231, v230
	v_add_f32_e32 v234, v235, v234
	v_add_f32_e32 v238, v239, v238
	v_add_f32_e32 v228, v228, v229
	v_add_f32_e32 v232, v232, v233
	v_add_f32_e32 v236, v236, v237
	v_add_f32_e32 v240, v240, v241
	v_add_f32_e32 v226, v226, v228
	v_add_f32_e32 v230, v230, v232
	v_add_f32_e32 v234, v234, v236
	v_add_f32_e32 v238, v238, v240
	ds_bpermute_b32 v227, v199, v226
	ds_bpermute_b32 v231, v199, v230
	ds_bpermute_b32 v235, v199, v234
	ds_bpermute_b32 v239, v199, v238
	s_waitcnt lgkmcnt(4)
	v_add_f32_e32 v210, v210, v211
	v_add_f32_e32 v214, v214, v215
	v_add_f32_e32 v218, v218, v219
	v_add_f32_e32 v222, v222, v223
	ds_bpermute_b32 v211, v200, v210
	ds_bpermute_b32 v215, v200, v214
	ds_bpermute_b32 v219, v200, v218
	ds_bpermute_b32 v223, v200, v222
	s_waitcnt lgkmcnt(4)
	v_add_f32_e32 v226, v226, v227
	v_add_f32_e32 v230, v230, v231
	v_add_f32_e32 v234, v234, v235
	v_add_f32_e32 v238, v238, v239
	ds_bpermute_b32 v227, v200, v226
	ds_bpermute_b32 v231, v200, v230
	ds_bpermute_b32 v235, v200, v234
	ds_bpermute_b32 v239, v200, v238
	s_waitcnt lgkmcnt(4)
	v_add_f32_e32 v210, v210, v211
	v_add_f32_e32 v214, v214, v215
	v_add_f32_e32 v218, v218, v219
	v_add_f32_e32 v222, v222, v223
	v_fmamk_f32 v210, v210, 0x3a800000, v140
	v_fmamk_f32 v214, v214, 0x3a800000, v140
	v_fmamk_f32 v218, v218, 0x3a800000, v140
	v_fmamk_f32 v222, v222, 0x3a800000, v140
	v_cmp_gt_f32_e64 vcc, s92, v210
	v_cmp_gt_f32_e64 s[6:7], s92, v214
	v_cmp_gt_f32_e64 s[40:41], s92, v218
	v_cmp_gt_f32_e64 s[42:43], s92, v222
	v_mul_f32_e32 v211, 0x4b800000, v210
	v_mul_f32_e32 v215, 0x4b800000, v214
	v_mul_f32_e32 v219, 0x4b800000, v218
	v_mul_f32_e32 v223, 0x4b800000, v222
	v_cndmask_b32_e64 v210, v210, v211, vcc
	v_cndmask_b32_e64 v214, v214, v215, s[6:7]
	v_cndmask_b32_e64 v218, v218, v219, s[40:41]
	v_cndmask_b32_e64 v222, v222, v223, s[42:43]
	v_rsq_f32_e32 v210, v210
	v_rsq_f32_e32 v214, v214
	v_rsq_f32_e32 v218, v218
	v_rsq_f32_e32 v222, v222
	v_mul_f32_e32 v211, 0x45800000, v210
	v_mul_f32_e32 v215, 0x45800000, v214
	v_mul_f32_e32 v219, 0x45800000, v218
	v_mul_f32_e32 v223, 0x45800000, v222
	v_cndmask_b32_e64 v210, v210, v211, vcc
	v_cndmask_b32_e64 v214, v214, v215, s[6:7]
	v_cndmask_b32_e64 v218, v218, v219, s[40:41]
	v_cndmask_b32_e64 v222, v222, v223, s[42:43]
	s_waitcnt lgkmcnt(0)
	v_add_f32_e32 v226, v226, v227
	v_add_f32_e32 v230, v230, v231
	v_add_f32_e32 v234, v234, v235
	v_add_f32_e32 v238, v238, v239
	v_fmamk_f32 v226, v226, 0x3a800000, v140
	v_fmamk_f32 v230, v230, 0x3a800000, v140
	v_fmamk_f32 v234, v234, 0x3a800000, v140
	v_fmamk_f32 v238, v238, 0x3a800000, v140
	v_cmp_gt_f32_e64 vcc, s92, v226
	v_cmp_gt_f32_e64 s[6:7], s92, v230
	v_cmp_gt_f32_e64 s[40:41], s92, v234
	v_cmp_gt_f32_e64 s[42:43], s92, v238
	v_mul_f32_e32 v227, 0x4b800000, v226
	v_mul_f32_e32 v231, 0x4b800000, v230
	v_mul_f32_e32 v235, 0x4b800000, v234
	v_mul_f32_e32 v239, 0x4b800000, v238
	v_cndmask_b32_e64 v226, v226, v227, vcc
	v_cndmask_b32_e64 v230, v230, v231, s[6:7]
	v_cndmask_b32_e64 v234, v234, v235, s[40:41]
	v_cndmask_b32_e64 v238, v238, v239, s[42:43]
	v_rsq_f32_e32 v226, v226
	v_rsq_f32_e32 v230, v230
	v_rsq_f32_e32 v234, v234
	v_rsq_f32_e32 v238, v238
	v_mul_f32_e32 v227, 0x45800000, v226
	v_mul_f32_e32 v231, 0x45800000, v230
	v_mul_f32_e32 v235, 0x45800000, v234
	v_mul_f32_e32 v239, 0x45800000, v238
	v_cndmask_b32_e64 v226, v226, v227, vcc
	v_cndmask_b32_e64 v230, v230, v231, s[6:7]
	v_cndmask_b32_e64 v234, v234, v235, s[40:41]
	v_cndmask_b32_e64 v238, v238, v239, s[42:43]
	s_cmp_gt_i32 s10, 31
	s_cbranch_scc1 .Lp3e_fa
	s_lshl_b32 s40, s36, 5
	s_mov_b32 s41, 0
	s_mul_i32 s42, s36, 0xa0
	s_mov_b32 s43, 0
	s_cmp_lg_u64 s[12:13], 0
	s_cbranch_scc1 .Lp3e_kv
; __device__ __forceinline__ unsigned cvt_pk_bf16(float lo, float hi) { f32x2_cv v = {lo, hi}; bf16x2_cv b = __builtin_convertvector(v, bf16x2_cv); return __builtin_bit_cast(unsigned, b); }
;     __device__ __forceinline__ void operator()(const f32x4 (&acc)[2][2][4][2], const Unit& u, int wr, int wc, int fr, int fq) const {
;     ...
;                 if (pn < 32) {
; #pragma unroll
;                     for (int bj = 0; bj < 2; ++bj) {
;                         const f32x4 v0 = acc[ai][bj][m][0] * rs, v1 = acc[ai][bj][m][1] * rs;
;                         u32x4 w; w.x = cvt_pk_bf16(v0[0], v0[1]); w.y = cvt_pk_bf16(v0[2], v0[3]); w.z = cvt_pk_bf16(v1[0], v1[1]); w.w = cvt_pk_bf16(v1[2], v1[3]);
;                         if (pn >= 24) __builtin_nontemporal_store(w, (u32x4*)(dst + (size_t)row * ldc + col0 + bj * HALF)); else *(u32x4*)(dst + (size_t)row * ldc + col0 + bj * HALF) = w;
	v_pk_mul_f32 v[128:129], v[128:129], v[210:211] op_sel_hi:[1,0]
	v_pk_mul_f32 v[130:131], v[130:131], v[210:211] op_sel_hi:[1,0]
	v_pk_mul_f32 v[124:125], v[124:125], v[210:211] op_sel_hi:[1,0]
	v_pk_mul_f32 v[126:127], v[126:127], v[210:211] op_sel_hi:[1,0]
	v_cvt_pk_bf16_f32 v182, v128, v129
	v_cvt_pk_bf16_f32 v183, v130, v131
	v_cvt_pk_bf16_f32 v184, v124, v125
	v_cvt_pk_bf16_f32 v185, v126, v127
	global_store_dwordx4 v[156:157], v[182:185], off
	v_pk_mul_f32 v[120:121], v[120:121], v[210:211] op_sel_hi:[1,0]
	v_pk_mul_f32 v[122:123], v[122:123], v[210:211] op_sel_hi:[1,0]
	v_pk_mul_f32 v[116:117], v[116:117], v[210:211] op_sel_hi:[1,0]
	v_pk_mul_f32 v[118:119], v[118:119], v[210:211] op_sel_hi:[1,0]
	v_cvt_pk_bf16_f32 v186, v120, v121
	v_cvt_pk_bf16_f32 v187, v122, v123
	v_cvt_pk_bf16_f32 v188, v116, v117
	v_cvt_pk_bf16_f32 v189, v118, v119
	global_store_dwordx4 v[156:157], v[186:189], off offset:256
	v_lshl_add_u64 v[156:157], v[156:157], 0, s[40:41]
	v_pk_mul_f32 v[112:113], v[112:113], v[214:215] op_sel_hi:[1,0]
	v_pk_mul_f32 v[114:115], v[114:115], v[214:215] op_sel_hi:[1,0]
	v_pk_mul_f32 v[108:109], v[108:109], v[214:215] op_sel_hi:[1,0]
	v_pk_mul_f32 v[110:111], v[110:111], v[214:215] op_sel_hi:[1,0]
	v_cvt_pk_bf16_f32 v190, v112, v113
	v_cvt_pk_bf16_f32 v191, v114, v115
	v_cvt_pk_bf16_f32 v192, v108, v109
	v_cvt_pk_bf16_f32 v193, v110, v111
	global_store_dwordx4 v[156:157], v[190:193], off
	v_pk_mul_f32 v[104:105], v[104:105], v[214:215] op_sel_hi:[1,0]
	v_pk_mul_f32 v[106:107], v[106:107], v[214:215] op_sel_hi:[1,0]
	v_pk_mul_f32 v[100:101], v[100:101], v[214:215] op_sel_hi:[1,0]
	v_pk_mul_f32 v[102:103], v[102:103], v[214:215] op_sel_hi:[1,0]
	v_cvt_pk_bf16_f32 v242, v104, v105
	v_cvt_pk_bf16_f32 v243, v106, v107
	v_cvt_pk_bf16_f32 v244, v100, v101
	v_cvt_pk_bf16_f32 v245, v102, v103
	global_store_dwordx4 v[156:157], v[242:245], off offset:256
	v_lshl_add_u64 v[156:157], v[156:157], 0, s[40:41]
	v_pk_mul_f32 v[96:97], v[96:97], v[218:219] op_sel_hi:[1,0]
	v_pk_mul_f32 v[98:99], v[98:99], v[218:219] op_sel_hi:[1,0]
	v_pk_mul_f32 v[92:93], v[92:93], v[218:219] op_sel_hi:[1,0]
	v_pk_mul_f32 v[94:95], v[94:95], v[218:219] op_sel_hi:[1,0]
	v_cvt_pk_bf16_f32 v182, v96, v97
	v_cvt_pk_bf16_f32 v183, v98, v99
	v_cvt_pk_bf16_f32 v184, v92, v93
	v_cvt_pk_bf16_f32 v185, v94, v95
	global_store_dwordx4 v[156:157], v[182:185], off
	v_pk_mul_f32 v[88:89], v[88:89], v[218:219] op_sel_hi:[1,0]
	v_pk_mul_f32 v[90:91], v[90:91], v[218:219] op_sel_hi:[1,0]
	v_pk_mul_f32 v[84:85], v[84:85], v[218:219] op_sel_hi:[1,0]
	v_pk_mul_f32 v[86:87], v[86:87], v[218:219] op_sel_hi:[1,0]
	v_cvt_pk_bf16_f32 v186, v88, v89
	v_cvt_pk_bf16_f32 v187, v90, v91
	v_cvt_pk_bf16_f32 v188, v84, v85
	v_cvt_pk_bf16_f32 v189, v86, v87
	global_store_dwordx4 v[156:157], v[186:189], off offset:256
	v_lshl_add_u64 v[156:157], v[156:157], 0, s[40:41]
	v_pk_mul_f32 v[80:81], v[80:81], v[222:223] op_sel_hi:[1,0]
	v_pk_mul_f32 v[82:83], v[82:83], v[222:223] op_sel_hi:[1,0]
	v_pk_mul_f32 v[76:77], v[76:77], v[222:223] op_sel_hi:[1,0]
	v_pk_mul_f32 v[78:79], v[78:79], v[222:223] op_sel_hi:[1,0]
	v_cvt_pk_bf16_f32 v190, v80, v81
	v_cvt_pk_bf16_f32 v191, v82, v83
	v_cvt_pk_bf16_f32 v192, v76, v77
	v_cvt_pk_bf16_f32 v193, v78, v79
	global_store_dwordx4 v[156:157], v[190:193], off
	v_pk_mul_f32 v[72:73], v[72:73], v[222:223] op_sel_hi:[1,0]
	v_pk_mul_f32 v[74:75], v[74:75], v[222:223] op_sel_hi:[1,0]
	v_pk_mul_f32 v[68:69], v[68:69], v[222:223] op_sel_hi:[1,0]
	v_pk_mul_f32 v[70:71], v[70:71], v[222:223] op_sel_hi:[1,0]
	v_cvt_pk_bf16_f32 v242, v72, v73
	v_cvt_pk_bf16_f32 v243, v74, v75
	v_cvt_pk_bf16_f32 v244, v68, v69
	v_cvt_pk_bf16_f32 v245, v70, v71
	global_store_dwordx4 v[156:157], v[242:245], off offset:256
	v_lshl_add_u64 v[156:157], v[156:157], 0, s[42:43]
	v_pk_mul_f32 v[64:65], v[64:65], v[226:227] op_sel_hi:[1,0]
	v_pk_mul_f32 v[66:67], v[66:67], v[226:227] op_sel_hi:[1,0]
	v_pk_mul_f32 v[60:61], v[60:61], v[226:227] op_sel_hi:[1,0]
	v_pk_mul_f32 v[62:63], v[62:63], v[226:227] op_sel_hi:[1,0]
	v_cvt_pk_bf16_f32 v182, v64, v65
	v_cvt_pk_bf16_f32 v183, v66, v67
	v_cvt_pk_bf16_f32 v184, v60, v61
	v_cvt_pk_bf16_f32 v185, v62, v63
	global_store_dwordx4 v[156:157], v[182:185], off
	v_pk_mul_f32 v[56:57], v[56:57], v[226:227] op_sel_hi:[1,0]
	v_pk_mul_f32 v[58:59], v[58:59], v[226:227] op_sel_hi:[1,0]
	v_pk_mul_f32 v[52:53], v[52:53], v[226:227] op_sel_hi:[1,0]
	v_pk_mul_f32 v[54:55], v[54:55], v[226:227] op_sel_hi:[1,0]
	v_cvt_pk_bf16_f32 v186, v56, v57
	v_cvt_pk_bf16_f32 v187, v58, v59
	v_cvt_pk_bf16_f32 v188, v52, v53
	v_cvt_pk_bf16_f32 v189, v54, v55
	global_store_dwordx4 v[156:157], v[186:189], off offset:256
	v_lshl_add_u64 v[156:157], v[156:157], 0, s[40:41]
	v_pk_mul_f32 v[48:49], v[48:49], v[230:231] op_sel_hi:[1,0]
	v_pk_mul_f32 v[50:51], v[50:51], v[230:231] op_sel_hi:[1,0]
	v_pk_mul_f32 v[44:45], v[44:45], v[230:231] op_sel_hi:[1,0]
	v_pk_mul_f32 v[46:47], v[46:47], v[230:231] op_sel_hi:[1,0]
	v_cvt_pk_bf16_f32 v190, v48, v49
	v_cvt_pk_bf16_f32 v191, v50, v51
	v_cvt_pk_bf16_f32 v192, v44, v45
	v_cvt_pk_bf16_f32 v193, v46, v47
	global_store_dwordx4 v[156:157], v[190:193], off
	v_pk_mul_f32 v[40:41], v[40:41], v[230:231] op_sel_hi:[1,0]
	v_pk_mul_f32 v[42:43], v[42:43], v[230:231] op_sel_hi:[1,0]
	v_pk_mul_f32 v[36:37], v[36:37], v[230:231] op_sel_hi:[1,0]
	v_pk_mul_f32 v[38:39], v[38:39], v[230:231] op_sel_hi:[1,0]
	v_cvt_pk_bf16_f32 v242, v40, v41
	v_cvt_pk_bf16_f32 v243, v42, v43
	v_cvt_pk_bf16_f32 v244, v36, v37
	v_cvt_pk_bf16_f32 v245, v38, v39
	global_store_dwordx4 v[156:157], v[242:245], off offset:256
	v_lshl_add_u64 v[156:157], v[156:157], 0, s[40:41]
; __device__ __forceinline__ unsigned cvt_pk_bf16(float lo, float hi) { f32x2_cv v = {lo, hi}; bf16x2_cv b = __builtin_convertvector(v, bf16x2_cv); return __builtin_bit_cast(unsigned, b); }
;     __device__ __forceinline__ void operator()(const f32x4 (&acc)[2][2][4][2], const Unit& u, int wr, int wc, int fr, int fq) const {
;     ...
;                 if (pn < 32) {
; #pragma unroll
;                     for (int bj = 0; bj < 2; ++bj) {
;                         const f32x4 v0 = acc[ai][bj][m][0] * rs, v1 = acc[ai][bj][m][1] * rs;
;                         u32x4 w; w.x = cvt_pk_bf16(v0[0], v0[1]); w.y = cvt_pk_bf16(v0[2], v0[3]); w.z = cvt_pk_bf16(v1[0], v1[1]); w.w = cvt_pk_bf16(v1[2], v1[3]);
;                         if (pn >= 24) __builtin_nontemporal_store(w, (u32x4*)(dst + (size_t)row * ldc + col0 + bj * HALF)); else *(u32x4*)(dst + (size_t)row * ldc + col0 + bj * HALF) = w;
;                         if (kvo) { float* p = kvo + (size_t)(kvrow0 + row) * 1024 + col0 + bj * HALF; __builtin_nontemporal_store(v0, (f32x4*)p); __builtin_nontemporal_store(v1, (f32x4*)(p + 4)); }
	v_pk_mul_f32 v[32:33], v[32:33], v[234:235] op_sel_hi:[1,0]
	v_pk_mul_f32 v[34:35], v[34:35], v[234:235] op_sel_hi:[1,0]
	v_pk_mul_f32 v[28:29], v[28:29], v[234:235] op_sel_hi:[1,0]
	v_pk_mul_f32 v[30:31], v[30:31], v[234:235] op_sel_hi:[1,0]
	v_cvt_pk_bf16_f32 v182, v32, v33
	v_cvt_pk_bf16_f32 v183, v34, v35
	v_cvt_pk_bf16_f32 v184, v28, v29
	v_cvt_pk_bf16_f32 v185, v30, v31
	global_store_dwordx4 v[156:157], v[182:185], off
	v_pk_mul_f32 v[24:25], v[24:25], v[234:235] op_sel_hi:[1,0]
	v_pk_mul_f32 v[26:27], v[26:27], v[234:235] op_sel_hi:[1,0]
	v_pk_mul_f32 v[20:21], v[20:21], v[234:235] op_sel_hi:[1,0]
	v_pk_mul_f32 v[22:23], v[22:23], v[234:235] op_sel_hi:[1,0]
	v_cvt_pk_bf16_f32 v186, v24, v25
	v_cvt_pk_bf16_f32 v187, v26, v27
	v_cvt_pk_bf16_f32 v188, v20, v21
	v_cvt_pk_bf16_f32 v189, v22, v23
	global_store_dwordx4 v[156:157], v[186:189], off offset:256
	v_lshl_add_u64 v[156:157], v[156:157], 0, s[40:41]
	v_pk_mul_f32 v[16:17], v[16:17], v[238:239] op_sel_hi:[1,0]
	v_pk_mul_f32 v[18:19], v[18:19], v[238:239] op_sel_hi:[1,0]
	v_pk_mul_f32 v[12:13], v[12:13], v[238:239] op_sel_hi:[1,0]
	v_pk_mul_f32 v[14:15], v[14:15], v[238:239] op_sel_hi:[1,0]
	v_cvt_pk_bf16_f32 v190, v16, v17
	v_cvt_pk_bf16_f32 v191, v18, v19
	v_cvt_pk_bf16_f32 v192, v12, v13
	v_cvt_pk_bf16_f32 v193, v14, v15
	global_store_dwordx4 v[156:157], v[190:193], off
	v_pk_mul_f32 v[8:9], v[8:9], v[238:239] op_sel_hi:[1,0]
	v_pk_mul_f32 v[10:11], v[10:11], v[238:239] op_sel_hi:[1,0]
	v_pk_mul_f32 v[4:5], v[4:5], v[238:239] op_sel_hi:[1,0]
	v_pk_mul_f32 v[6:7], v[6:7], v[238:239] op_sel_hi:[1,0]
	v_cvt_pk_bf16_f32 v242, v8, v9
	v_cvt_pk_bf16_f32 v243, v10, v11
	v_cvt_pk_bf16_f32 v244, v4, v5
	v_cvt_pk_bf16_f32 v245, v6, v7
	global_store_dwordx4 v[156:157], v[242:245], off offset:256
	s_branch .LBB0_446
.Lp3e_kv:
	s_mov_b64 s[6:7], 0x10000
	s_mov_b64 s[38:39], 0x50000
	v_pk_mul_f32 v[128:129], v[128:129], v[210:211] op_sel_hi:[1,0]
	v_pk_mul_f32 v[130:131], v[130:131], v[210:211] op_sel_hi:[1,0]
	v_pk_mul_f32 v[124:125], v[124:125], v[210:211] op_sel_hi:[1,0]
	v_pk_mul_f32 v[126:127], v[126:127], v[210:211] op_sel_hi:[1,0]
	v_cvt_pk_bf16_f32 v182, v128, v129
	v_cvt_pk_bf16_f32 v183, v130, v131
	v_cvt_pk_bf16_f32 v184, v124, v125
	v_cvt_pk_bf16_f32 v185, v126, v127
	global_store_dwordx4 v[156:157], v[182:185], off
	global_store_dwordx4 v[158:159], v[128:131], off nt
	global_store_dwordx4 v[158:159], v[124:127], off offset:16 nt
	v_pk_mul_f32 v[120:121], v[120:121], v[210:211] op_sel_hi:[1,0]
	v_pk_mul_f32 v[122:123], v[122:123], v[210:211] op_sel_hi:[1,0]
	v_pk_mul_f32 v[116:117], v[116:117], v[210:211] op_sel_hi:[1,0]
	v_pk_mul_f32 v[118:119], v[118:119], v[210:211] op_sel_hi:[1,0]
	v_cvt_pk_bf16_f32 v186, v120, v121
	v_cvt_pk_bf16_f32 v187, v122, v123
	v_cvt_pk_bf16_f32 v188, v116, v117
	v_cvt_pk_bf16_f32 v189, v118, v119
	global_store_dwordx4 v[156:157], v[186:189], off offset:256
	global_store_dwordx4 v[158:159], v[120:123], off offset:512 nt
	global_store_dwordx4 v[158:159], v[116:119], off offset:528 nt
	v_lshl_add_u64 v[156:157], v[156:157], 0, s[40:41]
	v_lshl_add_u64 v[158:159], v[158:159], 0, s[6:7]
	v_pk_mul_f32 v[112:113], v[112:113], v[214:215] op_sel_hi:[1,0]
	v_pk_mul_f32 v[114:115], v[114:115], v[214:215] op_sel_hi:[1,0]
	v_pk_mul_f32 v[108:109], v[108:109], v[214:215] op_sel_hi:[1,0]
	v_pk_mul_f32 v[110:111], v[110:111], v[214:215] op_sel_hi:[1,0]
	v_cvt_pk_bf16_f32 v190, v112, v113
	v_cvt_pk_bf16_f32 v191, v114, v115
	v_cvt_pk_bf16_f32 v192, v108, v109
	v_cvt_pk_bf16_f32 v193, v110, v111
	global_store_dwordx4 v[156:157], v[190:193], off
	global_store_dwordx4 v[158:159], v[112:115], off nt
	global_store_dwordx4 v[158:159], v[108:111], off offset:16 nt
	v_pk_mul_f32 v[104:105], v[104:105], v[214:215] op_sel_hi:[1,0]
	v_pk_mul_f32 v[106:107], v[106:107], v[214:215] op_sel_hi:[1,0]
	v_pk_mul_f32 v[100:101], v[100:101], v[214:215] op_sel_hi:[1,0]
	v_pk_mul_f32 v[102:103], v[102:103], v[214:215] op_sel_hi:[1,0]
	v_cvt_pk_bf16_f32 v242, v104, v105
	v_cvt_pk_bf16_f32 v243, v106, v107
	v_cvt_pk_bf16_f32 v244, v100, v101
	v_cvt_pk_bf16_f32 v245, v102, v103
	global_store_dwordx4 v[156:157], v[242:245], off offset:256
	global_store_dwordx4 v[158:159], v[104:107], off offset:512 nt
	global_store_dwordx4 v[158:159], v[100:103], off offset:528 nt
	v_lshl_add_u64 v[156:157], v[156:157], 0, s[40:41]
	v_lshl_add_u64 v[158:159], v[158:159], 0, s[6:7]
	v_pk_mul_f32 v[96:97], v[96:97], v[218:219] op_sel_hi:[1,0]
	v_pk_mul_f32 v[98:99], v[98:99], v[218:219] op_sel_hi:[1,0]
	v_pk_mul_f32 v[92:93], v[92:93], v[218:219] op_sel_hi:[1,0]
	v_pk_mul_f32 v[94:95], v[94:95], v[218:219] op_sel_hi:[1,0]
	v_cvt_pk_bf16_f32 v182, v96, v97
	v_cvt_pk_bf16_f32 v183, v98, v99
	v_cvt_pk_bf16_f32 v184, v92, v93
	v_cvt_pk_bf16_f32 v185, v94, v95
	global_store_dwordx4 v[156:157], v[182:185], off
	global_store_dwordx4 v[158:159], v[96:99], off nt
	global_store_dwordx4 v[158:159], v[92:95], off offset:16 nt
	v_pk_mul_f32 v[88:89], v[88:89], v[218:219] op_sel_hi:[1,0]
	v_pk_mul_f32 v[90:91], v[90:91], v[218:219] op_sel_hi:[1,0]
	v_pk_mul_f32 v[84:85], v[84:85], v[218:219] op_sel_hi:[1,0]
	v_pk_mul_f32 v[86:87], v[86:87], v[218:219] op_sel_hi:[1,0]
	v_cvt_pk_bf16_f32 v186, v88, v89
	v_cvt_pk_bf16_f32 v187, v90, v91
	v_cvt_pk_bf16_f32 v188, v84, v85
	v_cvt_pk_bf16_f32 v189, v86, v87
	global_store_dwordx4 v[156:157], v[186:189], off offset:256
	global_store_dwordx4 v[158:159], v[88:91], off offset:512 nt
	global_store_dwordx4 v[158:159], v[84:87], off offset:528 nt
	v_lshl_add_u64 v[156:157], v[156:157], 0, s[40:41]
	v_lshl_add_u64 v[158:159], v[158:159], 0, s[6:7]
	v_pk_mul_f32 v[80:81], v[80:81], v[222:223] op_sel_hi:[1,0]
; __device__ __forceinline__ unsigned cvt_pk_bf16(float lo, float hi) { f32x2_cv v = {lo, hi}; bf16x2_cv b = __builtin_convertvector(v, bf16x2_cv); return __builtin_bit_cast(unsigned, b); }
;     __device__ __forceinline__ void operator()(const f32x4 (&acc)[2][2][4][2], const Unit& u, int wr, int wc, int fr, int fq) const {
;     ...
;                 if (pn < 32) {
; #pragma unroll
;                     for (int bj = 0; bj < 2; ++bj) {
;                         const f32x4 v0 = acc[ai][bj][m][0] * rs, v1 = acc[ai][bj][m][1] * rs;
;                         u32x4 w; w.x = cvt_pk_bf16(v0[0], v0[1]); w.y = cvt_pk_bf16(v0[2], v0[3]); w.z = cvt_pk_bf16(v1[0], v1[1]); w.w = cvt_pk_bf16(v1[2], v1[3]);
;                         if (pn >= 24) __builtin_nontemporal_store(w, (u32x4*)(dst + (size_t)row * ldc + col0 + bj * HALF)); else *(u32x4*)(dst + (size_t)row * ldc + col0 + bj * HALF) = w;
;                         if (kvo) { float* p = kvo + (size_t)(kvrow0 + row) * 1024 + col0 + bj * HALF; __builtin_nontemporal_store(v0, (f32x4*)p); __builtin_nontemporal_store(v1, (f32x4*)(p + 4)); }
	v_pk_mul_f32 v[82:83], v[82:83], v[222:223] op_sel_hi:[1,0]
	v_pk_mul_f32 v[76:77], v[76:77], v[222:223] op_sel_hi:[1,0]
	v_pk_mul_f32 v[78:79], v[78:79], v[222:223] op_sel_hi:[1,0]
	v_cvt_pk_bf16_f32 v190, v80, v81
	v_cvt_pk_bf16_f32 v191, v82, v83
	v_cvt_pk_bf16_f32 v192, v76, v77
	v_cvt_pk_bf16_f32 v193, v78, v79
	global_store_dwordx4 v[156:157], v[190:193], off
	global_store_dwordx4 v[158:159], v[80:83], off nt
	global_store_dwordx4 v[158:159], v[76:79], off offset:16 nt
	v_pk_mul_f32 v[72:73], v[72:73], v[222:223] op_sel_hi:[1,0]
	v_pk_mul_f32 v[74:75], v[74:75], v[222:223] op_sel_hi:[1,0]
	v_pk_mul_f32 v[68:69], v[68:69], v[222:223] op_sel_hi:[1,0]
	v_pk_mul_f32 v[70:71], v[70:71], v[222:223] op_sel_hi:[1,0]
	v_cvt_pk_bf16_f32 v242, v72, v73
	v_cvt_pk_bf16_f32 v243, v74, v75
	v_cvt_pk_bf16_f32 v244, v68, v69
	v_cvt_pk_bf16_f32 v245, v70, v71
	global_store_dwordx4 v[156:157], v[242:245], off offset:256
	global_store_dwordx4 v[158:159], v[72:75], off offset:512 nt
	global_store_dwordx4 v[158:159], v[68:71], off offset:528 nt
	v_lshl_add_u64 v[156:157], v[156:157], 0, s[42:43]
	v_lshl_add_u64 v[158:159], v[158:159], 0, s[38:39]
	v_pk_mul_f32 v[64:65], v[64:65], v[226:227] op_sel_hi:[1,0]
	v_pk_mul_f32 v[66:67], v[66:67], v[226:227] op_sel_hi:[1,0]
	v_pk_mul_f32 v[60:61], v[60:61], v[226:227] op_sel_hi:[1,0]
	v_pk_mul_f32 v[62:63], v[62:63], v[226:227] op_sel_hi:[1,0]
	v_cvt_pk_bf16_f32 v182, v64, v65
	v_cvt_pk_bf16_f32 v183, v66, v67
	v_cvt_pk_bf16_f32 v184, v60, v61
	v_cvt_pk_bf16_f32 v185, v62, v63
	global_store_dwordx4 v[156:157], v[182:185], off
	global_store_dwordx4 v[158:159], v[64:67], off nt
	global_store_dwordx4 v[158:159], v[60:63], off offset:16 nt
	v_pk_mul_f32 v[56:57], v[56:57], v[226:227] op_sel_hi:[1,0]
	v_pk_mul_f32 v[58:59], v[58:59], v[226:227] op_sel_hi:[1,0]
	v_pk_mul_f32 v[52:53], v[52:53], v[226:227] op_sel_hi:[1,0]
	v_pk_mul_f32 v[54:55], v[54:55], v[226:227] op_sel_hi:[1,0]
	v_cvt_pk_bf16_f32 v186, v56, v57
	v_cvt_pk_bf16_f32 v187, v58, v59
	v_cvt_pk_bf16_f32 v188, v52, v53
	v_cvt_pk_bf16_f32 v189, v54, v55
	global_store_dwordx4 v[156:157], v[186:189], off offset:256
	global_store_dwordx4 v[158:159], v[56:59], off offset:512 nt
	global_store_dwordx4 v[158:159], v[52:55], off offset:528 nt
	v_lshl_add_u64 v[156:157], v[156:157], 0, s[40:41]
	v_lshl_add_u64 v[158:159], v[158:159], 0, s[6:7]
	v_pk_mul_f32 v[48:49], v[48:49], v[230:231] op_sel_hi:[1,0]
	v_pk_mul_f32 v[50:51], v[50:51], v[230:231] op_sel_hi:[1,0]
	v_pk_mul_f32 v[44:45], v[44:45], v[230:231] op_sel_hi:[1,0]
	v_pk_mul_f32 v[46:47], v[46:47], v[230:231] op_sel_hi:[1,0]
	v_cvt_pk_bf16_f32 v190, v48, v49
	v_cvt_pk_bf16_f32 v191, v50, v51
	v_cvt_pk_bf16_f32 v192, v44, v45
	v_cvt_pk_bf16_f32 v193, v46, v47
	global_store_dwordx4 v[156:157], v[190:193], off
	global_store_dwordx4 v[158:159], v[48:51], off nt
	global_store_dwordx4 v[158:159], v[44:47], off offset:16 nt
	v_pk_mul_f32 v[40:41], v[40:41], v[230:231] op_sel_hi:[1,0]
	v_pk_mul_f32 v[42:43], v[42:43], v[230:231] op_sel_hi:[1,0]
	v_pk_mul_f32 v[36:37], v[36:37], v[230:231] op_sel_hi:[1,0]
	v_pk_mul_f32 v[38:39], v[38:39], v[230:231] op_sel_hi:[1,0]
	v_cvt_pk_bf16_f32 v242, v40, v41
	v_cvt_pk_bf16_f32 v243, v42, v43
	v_cvt_pk_bf16_f32 v244, v36, v37
	v_cvt_pk_bf16_f32 v245, v38, v39
	global_store_dwordx4 v[156:157], v[242:245], off offset:256
	global_store_dwordx4 v[158:159], v[40:43], off offset:512 nt
	global_store_dwordx4 v[158:159], v[36:39], off offset:528 nt
	v_lshl_add_u64 v[156:157], v[156:157], 0, s[40:41]
	v_lshl_add_u64 v[158:159], v[158:159], 0, s[6:7]
	v_pk_mul_f32 v[32:33], v[32:33], v[234:235] op_sel_hi:[1,0]
	v_pk_mul_f32 v[34:35], v[34:35], v[234:235] op_sel_hi:[1,0]
	v_pk_mul_f32 v[28:29], v[28:29], v[234:235] op_sel_hi:[1,0]
	v_pk_mul_f32 v[30:31], v[30:31], v[234:235] op_sel_hi:[1,0]
	v_cvt_pk_bf16_f32 v182, v32, v33
	v_cvt_pk_bf16_f32 v183, v34, v35
	v_cvt_pk_bf16_f32 v184, v28, v29
	v_cvt_pk_bf16_f32 v185, v30, v31
	global_store_dwordx4 v[156:157], v[182:185], off
	global_store_dwordx4 v[158:159], v[32:35], off nt
	global_store_dwordx4 v[158:159], v[28:31], off offset:16 nt
	v_pk_mul_f32 v[24:25], v[24:25], v[234:235] op_sel_hi:[1,0]
	v_pk_mul_f32 v[26:27], v[26:27], v[234:235] op_sel_hi:[1,0]
	v_pk_mul_f32 v[20:21], v[20:21], v[234:235] op_sel_hi:[1,0]
	v_pk_mul_f32 v[22:23], v[22:23], v[234:235] op_sel_hi:[1,0]
	v_cvt_pk_bf16_f32 v186, v24, v25
	v_cvt_pk_bf16_f32 v187, v26, v27
	v_cvt_pk_bf16_f32 v188, v20, v21
	v_cvt_pk_bf16_f32 v189, v22, v23
	global_store_dwordx4 v[156:157], v[186:189], off offset:256
	global_store_dwordx4 v[158:159], v[24:27], off offset:512 nt
	global_store_dwordx4 v[158:159], v[20:23], off offset:528 nt
	v_lshl_add_u64 v[156:157], v[156:157], 0, s[40:41]
	v_lshl_add_u64 v[158:159], v[158:159], 0, s[6:7]
	v_pk_mul_f32 v[16:17], v[16:17], v[238:239] op_sel_hi:[1,0]
	v_pk_mul_f32 v[18:19], v[18:19], v[238:239] op_sel_hi:[1,0]
	v_pk_mul_f32 v[12:13], v[12:13], v[238:239] op_sel_hi:[1,0]
	v_pk_mul_f32 v[14:15], v[14:15], v[238:239] op_sel_hi:[1,0]
	v_cvt_pk_bf16_f32 v190, v16, v17
	v_cvt_pk_bf16_f32 v191, v18, v19
	v_cvt_pk_bf16_f32 v192, v12, v13
	v_cvt_pk_bf16_f32 v193, v14, v15
	global_store_dwordx4 v[156:157], v[190:193], off
	global_store_dwordx4 v[158:159], v[16:19], off nt
	global_store_dwordx4 v[158:159], v[12:15], off offset:16 nt
	v_pk_mul_f32 v[8:9], v[8:9], v[238:239] op_sel_hi:[1,0]
	v_pk_mul_f32 v[10:11], v[10:11], v[238:239] op_sel_hi:[1,0]
	v_pk_mul_f32 v[4:5], v[4:5], v[238:239] op_sel_hi:[1,0]
	v_pk_mul_f32 v[6:7], v[6:7], v[238:239] op_sel_hi:[1,0]
	v_cvt_pk_bf16_f32 v242, v8, v9
	v_cvt_pk_bf16_f32 v243, v10, v11
	v_cvt_pk_bf16_f32 v244, v4, v5
	v_cvt_pk_bf16_f32 v245, v6, v7
	global_store_dwordx4 v[156:157], v[242:245], off offset:256
	global_store_dwordx4 v[158:159], v[8:11], off offset:512 nt
	global_store_dwordx4 v[158:159], v[4:7], off offset:528 nt
	s_branch .LBB0_446
;     __device__ __forceinline__ void operator()(const f32x4 (&acc)[2][2][4][2], const Unit& u, int wr, int wc, int fr, int fq) const {
;     ...
;                 } else if (wc == 0 && fq < 2) {
;                     const f32x4 v0 = acc[ai][0][m][0] * rs, v1 = acc[ai][0][m][1] * rs;
;                     float* p = FA + (size_t)row * 16 + 8 * fq; *(f32x4*)p = v0; *(f32x4*)(p + 4) = v1;
;                 }
.Lp3e_fa:
	s_and_saveexec_b64 s[42:43], s[24:25]
	v_pk_mul_f32 v[128:129], v[128:129], v[210:211] op_sel_hi:[1,0]
	v_pk_mul_f32 v[130:131], v[130:131], v[210:211] op_sel_hi:[1,0]
	v_pk_mul_f32 v[124:125], v[124:125], v[210:211] op_sel_hi:[1,0]
	v_pk_mul_f32 v[126:127], v[126:127], v[210:211] op_sel_hi:[1,0]
	global_store_dwordx4 v[160:161], v[128:131], off
	global_store_dwordx4 v[160:161], v[124:127], off offset:16
	v_pk_mul_f32 v[112:113], v[112:113], v[214:215] op_sel_hi:[1,0]
	v_pk_mul_f32 v[114:115], v[114:115], v[214:215] op_sel_hi:[1,0]
	v_pk_mul_f32 v[108:109], v[108:109], v[214:215] op_sel_hi:[1,0]
	v_pk_mul_f32 v[110:111], v[110:111], v[214:215] op_sel_hi:[1,0]
	global_store_dwordx4 v[160:161], v[112:115], off offset:1024
	global_store_dwordx4 v[160:161], v[108:111], off offset:1040
	v_pk_mul_f32 v[96:97], v[96:97], v[218:219] op_sel_hi:[1,0]
	v_pk_mul_f32 v[98:99], v[98:99], v[218:219] op_sel_hi:[1,0]
	v_pk_mul_f32 v[92:93], v[92:93], v[218:219] op_sel_hi:[1,0]
	v_pk_mul_f32 v[94:95], v[94:95], v[218:219] op_sel_hi:[1,0]
	global_store_dwordx4 v[160:161], v[96:99], off offset:2048
	global_store_dwordx4 v[160:161], v[92:95], off offset:2064
	v_pk_mul_f32 v[80:81], v[80:81], v[222:223] op_sel_hi:[1,0]
	v_pk_mul_f32 v[82:83], v[82:83], v[222:223] op_sel_hi:[1,0]
	v_pk_mul_f32 v[76:77], v[76:77], v[222:223] op_sel_hi:[1,0]
	v_pk_mul_f32 v[78:79], v[78:79], v[222:223] op_sel_hi:[1,0]
	global_store_dwordx4 v[160:161], v[80:83], off offset:3072
	global_store_dwordx4 v[160:161], v[76:79], off offset:3088
	v_pk_mul_f32 v[64:65], v[64:65], v[226:227] op_sel_hi:[1,0]
	v_pk_mul_f32 v[66:67], v[66:67], v[226:227] op_sel_hi:[1,0]
	v_pk_mul_f32 v[60:61], v[60:61], v[226:227] op_sel_hi:[1,0]
	v_pk_mul_f32 v[62:63], v[62:63], v[226:227] op_sel_hi:[1,0]
	global_store_dwordx4 v[162:163], v[64:67], off
	global_store_dwordx4 v[162:163], v[60:63], off offset:16
	v_pk_mul_f32 v[48:49], v[48:49], v[230:231] op_sel_hi:[1,0]
	v_pk_mul_f32 v[50:51], v[50:51], v[230:231] op_sel_hi:[1,0]
	v_pk_mul_f32 v[44:45], v[44:45], v[230:231] op_sel_hi:[1,0]
	v_pk_mul_f32 v[46:47], v[46:47], v[230:231] op_sel_hi:[1,0]
	global_store_dwordx4 v[162:163], v[48:51], off offset:1024
	global_store_dwordx4 v[162:163], v[44:47], off offset:1040
	v_pk_mul_f32 v[32:33], v[32:33], v[234:235] op_sel_hi:[1,0]
	v_pk_mul_f32 v[34:35], v[34:35], v[234:235] op_sel_hi:[1,0]
	v_pk_mul_f32 v[28:29], v[28:29], v[234:235] op_sel_hi:[1,0]
	v_pk_mul_f32 v[30:31], v[30:31], v[234:235] op_sel_hi:[1,0]
	global_store_dwordx4 v[162:163], v[32:35], off offset:2048
	global_store_dwordx4 v[162:163], v[28:31], off offset:2064
	v_pk_mul_f32 v[16:17], v[16:17], v[238:239] op_sel_hi:[1,0]
	v_pk_mul_f32 v[18:19], v[18:19], v[238:239] op_sel_hi:[1,0]
	v_pk_mul_f32 v[12:13], v[12:13], v[238:239] op_sel_hi:[1,0]
	v_pk_mul_f32 v[14:15], v[14:15], v[238:239] op_sel_hi:[1,0]
	global_store_dwordx4 v[162:163], v[16:19], off offset:3072
	global_store_dwordx4 v[162:163], v[12:15], off offset:3088
	s_mov_b64 exec, s[42:43]
